# RG-LRU carry application folded per 4-row run: E'=Eg+Fg*Ew, F'=Fg*Fw once, per element out=bv+av*E', cqw=av*F' (24 VALU ops fewer per sub-block; f32 reassociation)
# speedup vs baseline: 1.0059x; 1.0005x over previous
.LBB0_270:
	v_cndmask_b32_e64 v0, 1.0, v35, s[4:5]
	v_cndmask_b32_e64 v35, 0, v37, s[4:5]
	v_fmac_f32_e32 v35, v0, v1
	v_mul_f32_e32 v0, v0, v8
	v_cndmask_b32_e64 v37, v38, v41, s[4:5]
	v_cndmask_b32_e64 v36, v36, v40, s[4:5]
	v_fmac_f32_e32 v36, v37, v1
	v_mul_f32_e32 v37, v37, v8
	v_cndmask_b32_e64 v40, v46, v88, s[4:5]
	v_cndmask_b32_e64 v41, v43, v47, s[4:5]
	v_fmac_f32_e32 v41, v40, v1
	v_mul_f32_e32 v40, v40, v8
	s_ashr_i32 s13, s12, 31
	v_lshlrev_b32_e32 v88, 2, v93
	v_fmac_f32_e32 v25, v32, v41
	v_mul_f32_e32 v32, v32, v40
	v_fmac_f32_e32 v9, v34, v36
	v_mul_f32_e32 v34, v34, v37
	v_fmac_f32_e32 v10, v31, v36
	v_mul_f32_e32 v31, v31, v37
	v_fmac_f32_e32 v5, v28, v36
	v_mul_f32_e32 v28, v28, v37
	v_fmac_f32_e32 v11, v18, v36
	v_mul_f32_e32 v18, v18, v37
	v_fmac_f32_e32 v6, v12, v35
	v_mul_f32_e32 v36, v0, v12
	v_fmac_f32_e32 v4, v13, v35
	v_mul_f32_e32 v37, v0, v13
	v_lshl_add_u64 v[12:13], s[24:25], 0, v[88:89]
	s_lshl_b64 s[6:7], s[12:13], 12
	v_lshl_add_u64 v[94:95], v[12:13], 0, s[6:7]
	v_fmac_f32_e32 v23, v29, v41
	v_mul_f32_e32 v29, v29, v40
	v_fmac_f32_e32 v21, v26, v41
	v_mul_f32_e32 v26, v26, v40
	v_fmac_f32_e32 v3, v16, v41
	v_mul_f32_e32 v40, v16, v40
	v_lshlrev_b32_e32 v12, 14, v92
	v_cvt_pk_bf16_f32 v16, v25, v32
	v_mov_b32_e32 v13, v89
	v_cndmask_b32_e64 v38, v42, v45, s[4:5]
	v_cndmask_b32_e64 v39, v39, v44, s[4:5]
	v_fmac_f32_e32 v39, v38, v1
	v_mul_f32_e32 v38, v38, v8
	v_lshl_add_u64 v[96:97], v[94:95], 0, v[12:13]
	v_or_b32_e32 v88, 0x1000, v12
	v_fmac_f32_e32 v22, v33, v39
	v_mul_f32_e32 v33, v33, v38
	v_fmac_f32_e32 v20, v30, v39
	v_mul_f32_e32 v30, v30, v38
	v_fmac_f32_e32 v19, v27, v39
	v_mul_f32_e32 v27, v27, v38
	v_fmac_f32_e32 v7, v17, v39
	v_mul_f32_e32 v38, v17, v38
	v_lshl_or_b32 v175, v138, 2, v133
	global_load_dword v172, v175, s[42:43]
	global_load_dword v173, v175, s[36:37]
	global_load_dword v174, v175, s[40:41]
	global_store_dword v[96:97], v16, off nt
	v_cvt_pk_bf16_f32 v13, v23, v29
	v_lshl_add_u64 v[16:17], v[94:95], 0, v[88:89]
	global_store_dword v[16:17], v13, off nt
	v_or_b32_e32 v98, 0x2000, v12
	v_mov_b32_e32 v99, v89
	v_cvt_pk_bf16_f32 v13, v21, v26
	v_lshl_add_u64 v[16:17], v[94:95], 0, v[98:99]
	v_or_b32_e32 v100, 0x3000, v12
	v_mov_b32_e32 v101, v89
	global_store_dword v[16:17], v13, off nt
	v_cvt_pk_bf16_f32 v3, v3, v40
	v_lshl_add_u64 v[16:17], v[94:95], 0, v[100:101]
	global_store_dword v[16:17], v3, off nt
	v_or_b32_e32 v102, 0x8000, v12
	v_mov_b32_e32 v103, v89
	v_cvt_pk_bf16_f32 v3, v22, v33
	v_lshl_add_u64 v[16:17], v[94:95], 0, v[102:103]
	global_store_dword v[16:17], v3, off nt
	v_or_b32_e32 v104, 0x9000, v12
	v_mov_b32_e32 v105, v89
	v_cvt_pk_bf16_f32 v3, v20, v30
	v_lshl_add_u64 v[16:17], v[94:95], 0, v[104:105]
	global_store_dword v[16:17], v3, off nt
	v_or_b32_e32 v106, 0xa000, v12
	v_mov_b32_e32 v107, v89
	v_cvt_pk_bf16_f32 v3, v19, v27
	v_lshl_add_u64 v[16:17], v[94:95], 0, v[106:107]
	global_store_dword v[16:17], v3, off nt
	v_or_b32_e32 v108, 0xb000, v12
	v_mov_b32_e32 v109, v89
	v_cvt_pk_bf16_f32 v3, v7, v38
	v_lshl_add_u64 v[16:17], v[94:95], 0, v[108:109]
	global_store_dword v[16:17], v3, off nt
	v_or_b32_e32 v110, 0x10000, v12
	v_mov_b32_e32 v111, v89
	v_cvt_pk_bf16_f32 v3, v9, v34
	v_lshl_add_u64 v[16:17], v[94:95], 0, v[110:111]
	global_store_dword v[16:17], v3, off nt
	v_or_b32_e32 v112, 0x11000, v12
	v_mov_b32_e32 v113, v89
	v_cvt_pk_bf16_f32 v3, v10, v31
	v_lshl_add_u64 v[16:17], v[94:95], 0, v[112:113]
	global_store_dword v[16:17], v3, off nt
	v_or_b32_e32 v114, 0x12000, v12
	v_mov_b32_e32 v115, v89
	v_cvt_pk_bf16_f32 v3, v5, v28
	v_lshl_add_u64 v[16:17], v[94:95], 0, v[114:115]
	global_store_dword v[16:17], v3, off nt
	v_or_b32_e32 v116, 0x13000, v12
	v_mov_b32_e32 v117, v89
	v_cvt_pk_bf16_f32 v3, v11, v18
	v_lshl_add_u64 v[10:11], v[94:95], 0, v[116:117]
	global_store_dword v[10:11], v3, off nt
	v_or_b32_e32 v118, 0x18000, v12
	v_mov_b32_e32 v119, v89
	v_cvt_pk_bf16_f32 v3, v6, v36
	v_lshl_add_u64 v[6:7], v[94:95], 0, v[118:119]
	global_store_dword v[6:7], v3, off nt
	v_or_b32_e32 v120, 0x19000, v12
	v_mov_b32_e32 v121, v89
	v_fmac_f32_e32 v2, v14, v35
	v_mul_f32_e32 v14, v0, v14
	v_cvt_pk_bf16_f32 v3, v4, v37
	v_lshl_add_u64 v[4:5], v[94:95], 0, v[120:121]
	v_fmac_f32_e32 v15, v24, v35
	v_mul_f32_e32 v0, v0, v24
	s_lshl_b32 s8, s65, 11
	global_store_dword v[4:5], v3, off nt
	v_or_b32_e32 v122, 0x1a000, v12
	v_mov_b32_e32 v123, v89
	s_or_b32 s8, s8, s76
	v_cvt_pk_bf16_f32 v4, v2, v14
	v_lshl_add_u64 v[2:3], v[94:95], 0, v[122:123]
	v_or_b32_e32 v124, 0x1b000, v12
	v_mov_b32_e32 v125, v89
	v_cmp_gt_i32_e64 s[6:7], 32, v90
	v_add_u32_e32 v92, s8, v90
	global_store_dword v[2:3], v4, off nt
	v_cvt_pk_bf16_f32 v2, v15, v0
	v_lshl_add_u64 v[0:1], v[94:95], 0, v[124:125]
	v_lshl_add_u32 v90, v90, 3, 16
	global_store_dword v[0:1], v2, off nt
	s_and_saveexec_b64 s[8:9], s[6:7]
	s_cbranch_execz .LBB0_272
	ds_read2_b64 v[0:3], v90 offset0:192 offset1:224
	ds_read2_b64 v[4:7], v90 offset0:128 offset1:160
	ds_read2_b64 v[8:11], v90 offset0:64 offset1:96
	ds_read2_b64 v[12:15], v90 offset1:32
	v_ashrrev_i32_e32 v93, 31, v92
	s_waitcnt lgkmcnt(3)
	v_fma_f32 v16, 0, v2, v3
	v_pk_mul_f32 v[2:3], v[2:3], v[0:1]
	v_fma_f32 v0, v0, v16, v1
	s_waitcnt lgkmcnt(2)
	v_fma_f32 v0, v6, v0, v7
	v_fma_f32 v0, v4, v0, v5
	s_waitcnt lgkmcnt(1)
	v_fma_f32 v1, v10, v0, v11
	v_mov_b32_e32 v0, v2
	v_mov_b32_e32 v16, v6
	v_mov_b32_e32 v17, v8
	v_pk_mul_f32 v[2:3], v[2:3], v[6:7]
	v_pk_fma_f32 v[0:1], v[0:1], v[16:17], v[8:9]
	v_pk_mul_f32 v[2:3], v[2:3], v[4:5]
	s_waitcnt lgkmcnt(0)
	v_mov_b32_e32 v11, v14
	v_mov_b32_e32 v3, v1
	v_pk_mul_f32 v[0:1], v[2:3], v[10:11]
	v_pk_fma_f32 v[2:3], v[2:3], v[10:11], v[14:15]
	v_pk_mul_f32 v[0:1], v[0:1], v[8:9]
	v_mov_b32_e32 v4, v14
	v_mov_b32_e32 v2, v0
	v_mov_b32_e32 v5, v12
	v_pk_mul_f32 v[0:1], v[0:1], v[14:15]
	v_pk_fma_f32 v[2:3], v[2:3], v[4:5], v[12:13]
	v_pk_mul_f32 v[0:1], v[0:1], v[12:13]
	s_nop 0
	v_mov_b32_e32 v1, v3
	v_lshl_add_u64 v[2:3], v[92:93], 3, s[30:31]
	global_store_dwordx2 v[2:3], v[0:1], off

.LBB0_278:
	v_cndmask_b32_e64 v0, 1.0, v35, s[4:5]
	v_cndmask_b32_e64 v35, 0, v37, s[4:5]
	v_fmac_f32_e32 v35, v0, v1
	v_mul_f32_e32 v0, v0, v8
	v_cndmask_b32_e64 v37, v38, v41, s[4:5]
	v_cndmask_b32_e64 v36, v36, v40, s[4:5]
	v_fmac_f32_e32 v36, v37, v1
	v_mul_f32_e32 v37, v37, v8
	v_cndmask_b32_e64 v40, v46, v93, s[4:5]
	v_cndmask_b32_e64 v41, v43, v47, s[4:5]
	v_fmac_f32_e32 v41, v40, v1
	v_mul_f32_e32 v40, v40, v8
	v_fmac_f32_e32 v25, v32, v41
	v_mul_f32_e32 v32, v32, v40
	v_fmac_f32_e32 v23, v29, v41
	v_mul_f32_e32 v29, v29, v40
	v_fmac_f32_e32 v20, v26, v41
	v_mul_f32_e32 v26, v26, v40
	v_fmac_f32_e32 v3, v16, v41
	v_mul_f32_e32 v40, v16, v40
	v_cvt_pk_bf16_f32 v16, v25, v32
	v_cndmask_b32_e64 v38, v42, v45, s[4:5]
	v_cndmask_b32_e64 v39, v39, v44, s[4:5]
	v_fmac_f32_e32 v39, v38, v1
	v_mul_f32_e32 v38, v38, v8
	v_fmac_f32_e32 v10, v34, v36
	v_mul_f32_e32 v34, v34, v37
	v_fmac_f32_e32 v6, v31, v36
	v_mul_f32_e32 v31, v31, v37
	v_fmac_f32_e32 v4, v28, v36
	v_mul_f32_e32 v28, v28, v37
	v_fmac_f32_e32 v11, v18, v36
	v_mul_f32_e32 v18, v18, v37
	v_fmac_f32_e32 v9, v12, v35
	v_mul_f32_e32 v36, v0, v12
	v_fmac_f32_e32 v5, v13, v35
	v_mul_f32_e32 v37, v0, v13
	v_lshl_add_u64 v[12:13], v[94:95], 0, s[48:49]
	v_lshl_or_b32 v175, v138, 2, v134
	global_load_dword v172, v175, s[42:43]
	global_load_dword v173, v175, s[36:37]
	global_load_dword v174, v175, s[40:41]
	global_store_dword v[96:97], v16, off offset:128 nt
	v_fmac_f32_e32 v24, v33, v39
	v_mul_f32_e32 v33, v33, v38
	v_fmac_f32_e32 v21, v30, v39
	v_mul_f32_e32 v30, v30, v38
	v_fmac_f32_e32 v19, v27, v39
	v_mul_f32_e32 v27, v27, v38
	v_fmac_f32_e32 v7, v17, v39
	v_mul_f32_e32 v38, v17, v38
	v_fmac_f32_e32 v2, v14, v35
	v_mul_f32_e32 v14, v0, v14
	v_fmac_f32_e32 v15, v22, v35
	v_mul_f32_e32 v0, v0, v22
	v_cvt_pk_bf16_f32 v22, v23, v29
	v_lshl_add_u64 v[16:17], v[12:13], 0, v[88:89]
	global_store_dword v[16:17], v22, off nt
	v_cvt_pk_bf16_f32 v20, v20, v26
	v_lshl_add_u64 v[16:17], v[12:13], 0, v[98:99]
	global_store_dword v[16:17], v20, off nt
	v_cvt_pk_bf16_f32 v3, v3, v40
	v_lshl_add_u64 v[16:17], v[12:13], 0, v[100:101]
	global_store_dword v[16:17], v3, off nt
	v_cvt_pk_bf16_f32 v3, v24, v33
	v_lshl_add_u64 v[16:17], v[12:13], 0, v[102:103]
	global_store_dword v[16:17], v3, off nt
	v_cvt_pk_bf16_f32 v3, v21, v30
	v_lshl_add_u64 v[16:17], v[12:13], 0, v[104:105]
	global_store_dword v[16:17], v3, off nt
	v_cvt_pk_bf16_f32 v3, v19, v27
	v_lshl_add_u64 v[16:17], v[12:13], 0, v[106:107]
	global_store_dword v[16:17], v3, off nt
	v_cvt_pk_bf16_f32 v3, v7, v38
	v_lshl_add_u64 v[16:17], v[12:13], 0, v[108:109]
	global_store_dword v[16:17], v3, off nt
	v_cvt_pk_bf16_f32 v3, v10, v34
	v_lshl_add_u64 v[16:17], v[12:13], 0, v[110:111]
	global_store_dword v[16:17], v3, off nt
	v_cvt_pk_bf16_f32 v3, v6, v31
	v_lshl_add_u64 v[6:7], v[12:13], 0, v[112:113]
	global_store_dword v[6:7], v3, off nt
	v_cvt_pk_bf16_f32 v3, v4, v28
	v_lshl_add_u64 v[6:7], v[12:13], 0, v[114:115]
	global_store_dword v[6:7], v3, off nt
	v_cvt_pk_bf16_f32 v3, v11, v18
	v_lshl_add_u64 v[6:7], v[12:13], 0, v[116:117]
	global_store_dword v[6:7], v3, off nt
	v_cvt_pk_bf16_f32 v3, v9, v36
	v_lshl_add_u64 v[6:7], v[12:13], 0, v[118:119]
	global_store_dword v[6:7], v3, off nt
	v_cvt_pk_bf16_f32 v3, v5, v37
	v_lshl_add_u64 v[4:5], v[12:13], 0, v[120:121]
	global_store_dword v[4:5], v3, off nt
	v_cvt_pk_bf16_f32 v4, v2, v14
	v_lshl_add_u64 v[2:3], v[12:13], 0, v[122:123]
	global_store_dword v[2:3], v4, off nt
	v_cvt_pk_bf16_f32 v2, v15, v0
	v_lshl_add_u64 v[0:1], v[12:13], 0, v[124:125]
	global_store_dword v[0:1], v2, off nt
	s_and_saveexec_b64 s[12:13], s[6:7]
	s_cbranch_execz .LBB0_280
	v_add_u32_e32 v12, 0x800, v90
	ds_read2_b64 v[0:3], v12 offset0:192 offset1:224
	ds_read2_b64 v[4:7], v12 offset0:128 offset1:160
	ds_read2_b64 v[8:11], v12 offset0:64 offset1:96
	ds_read2_b64 v[12:15], v12 offset1:32
	s_waitcnt lgkmcnt(3)
	v_fma_f32 v16, 0, v2, v3
	v_pk_mul_f32 v[2:3], v[2:3], v[0:1]
	v_fma_f32 v0, v0, v16, v1
	s_waitcnt lgkmcnt(2)
	v_fma_f32 v0, v6, v0, v7
	v_fma_f32 v0, v4, v0, v5
	s_waitcnt lgkmcnt(1)
	v_fma_f32 v1, v10, v0, v11
	v_mov_b32_e32 v0, v2
	v_mov_b32_e32 v16, v6
	v_mov_b32_e32 v17, v8
	v_pk_mul_f32 v[2:3], v[2:3], v[6:7]
	v_pk_fma_f32 v[0:1], v[0:1], v[16:17], v[8:9]
	v_pk_mul_f32 v[2:3], v[2:3], v[4:5]
	s_waitcnt lgkmcnt(0)
	v_mov_b32_e32 v11, v14
	v_mov_b32_e32 v3, v1
	v_pk_mul_f32 v[0:1], v[2:3], v[10:11]
	v_pk_fma_f32 v[2:3], v[2:3], v[10:11], v[14:15]
	v_pk_mul_f32 v[0:1], v[0:1], v[8:9]
	v_mov_b32_e32 v4, v14
	v_mov_b32_e32 v2, v0
	v_mov_b32_e32 v5, v12
	v_pk_mul_f32 v[0:1], v[0:1], v[14:15]
	v_pk_fma_f32 v[2:3], v[2:3], v[4:5], v[12:13]
	v_pk_mul_f32 v[0:1], v[0:1], v[12:13]
	v_add_u32_e32 v2, 32, v92
	v_mov_b32_e32 v1, v3
	v_ashrrev_i32_e32 v3, 31, v2
	v_lshl_add_u64 v[2:3], v[2:3], 3, s[30:31]
	global_store_dwordx2 v[2:3], v[0:1], off

.LBB0_286:
	v_cndmask_b32_e64 v0, 1.0, v35, s[4:5]
	v_cndmask_b32_e64 v35, 0, v37, s[4:5]
	v_fmac_f32_e32 v35, v0, v1
	v_mul_f32_e32 v0, v0, v8
	v_cndmask_b32_e64 v37, v38, v41, s[4:5]
	v_cndmask_b32_e64 v36, v36, v40, s[4:5]
	v_fmac_f32_e32 v36, v37, v1
	v_mul_f32_e32 v37, v37, v8
	v_cndmask_b32_e64 v40, v46, v93, s[4:5]
	v_cndmask_b32_e64 v41, v43, v47, s[4:5]
	v_fmac_f32_e32 v41, v40, v1
	v_mul_f32_e32 v40, v40, v8
	v_fmac_f32_e32 v25, v32, v41
	v_mul_f32_e32 v32, v32, v40
	v_fmac_f32_e32 v23, v29, v41
	v_mul_f32_e32 v29, v29, v40
	v_fmac_f32_e32 v20, v26, v41
	v_mul_f32_e32 v26, v26, v40
	v_fmac_f32_e32 v3, v16, v41
	v_mul_f32_e32 v40, v16, v40
	v_cvt_pk_bf16_f32 v16, v25, v32
	v_cndmask_b32_e64 v38, v42, v45, s[4:5]
	v_cndmask_b32_e64 v39, v39, v44, s[4:5]
	v_fmac_f32_e32 v39, v38, v1
	v_mul_f32_e32 v38, v38, v8
	v_fmac_f32_e32 v10, v34, v36
	v_mul_f32_e32 v34, v34, v37
	v_fmac_f32_e32 v6, v31, v36
	v_mul_f32_e32 v31, v31, v37
	v_fmac_f32_e32 v4, v28, v36
	v_mul_f32_e32 v28, v28, v37
	v_fmac_f32_e32 v11, v18, v36
	v_mul_f32_e32 v18, v18, v37
	v_fmac_f32_e32 v9, v12, v35
	v_mul_f32_e32 v36, v0, v12
	v_fmac_f32_e32 v5, v13, v35
	v_mul_f32_e32 v37, v0, v13
	v_lshl_add_u64 v[12:13], v[94:95], 0, s[60:61]
	v_lshl_or_b32 v175, v138, 2, v135
	global_load_dword v172, v175, s[42:43]
	global_load_dword v173, v175, s[36:37]
	global_load_dword v174, v175, s[40:41]
	global_store_dword v[96:97], v16, off offset:256 nt
	v_fmac_f32_e32 v24, v33, v39
	v_mul_f32_e32 v33, v33, v38
	v_fmac_f32_e32 v21, v30, v39
	v_mul_f32_e32 v30, v30, v38
	v_fmac_f32_e32 v19, v27, v39
	v_mul_f32_e32 v27, v27, v38
	v_fmac_f32_e32 v7, v17, v39
	v_mul_f32_e32 v38, v17, v38
	v_fmac_f32_e32 v2, v14, v35
	v_mul_f32_e32 v14, v0, v14
	v_fmac_f32_e32 v15, v22, v35
	v_mul_f32_e32 v0, v0, v22
	v_cvt_pk_bf16_f32 v22, v23, v29
	v_lshl_add_u64 v[16:17], v[12:13], 0, v[88:89]
	global_store_dword v[16:17], v22, off nt
	v_cvt_pk_bf16_f32 v20, v20, v26
	v_lshl_add_u64 v[16:17], v[12:13], 0, v[98:99]
	global_store_dword v[16:17], v20, off nt
	v_cvt_pk_bf16_f32 v3, v3, v40
	v_lshl_add_u64 v[16:17], v[12:13], 0, v[100:101]
	global_store_dword v[16:17], v3, off nt
	v_cvt_pk_bf16_f32 v3, v24, v33
	v_lshl_add_u64 v[16:17], v[12:13], 0, v[102:103]
	global_store_dword v[16:17], v3, off nt
	v_cvt_pk_bf16_f32 v3, v21, v30
	v_lshl_add_u64 v[16:17], v[12:13], 0, v[104:105]
	global_store_dword v[16:17], v3, off nt
	v_cvt_pk_bf16_f32 v3, v19, v27
	v_lshl_add_u64 v[16:17], v[12:13], 0, v[106:107]
	global_store_dword v[16:17], v3, off nt
	v_cvt_pk_bf16_f32 v3, v7, v38
	v_lshl_add_u64 v[16:17], v[12:13], 0, v[108:109]
	global_store_dword v[16:17], v3, off nt
	v_cvt_pk_bf16_f32 v3, v10, v34
	v_lshl_add_u64 v[16:17], v[12:13], 0, v[110:111]
	global_store_dword v[16:17], v3, off nt
	v_cvt_pk_bf16_f32 v3, v6, v31
	v_lshl_add_u64 v[6:7], v[12:13], 0, v[112:113]
	global_store_dword v[6:7], v3, off nt
	v_cvt_pk_bf16_f32 v3, v4, v28
	v_lshl_add_u64 v[6:7], v[12:13], 0, v[114:115]
	global_store_dword v[6:7], v3, off nt
	v_cvt_pk_bf16_f32 v3, v11, v18
	v_lshl_add_u64 v[6:7], v[12:13], 0, v[116:117]
	global_store_dword v[6:7], v3, off nt
	v_cvt_pk_bf16_f32 v3, v9, v36
	v_lshl_add_u64 v[6:7], v[12:13], 0, v[118:119]
	global_store_dword v[6:7], v3, off nt
	v_cvt_pk_bf16_f32 v3, v5, v37
	v_lshl_add_u64 v[4:5], v[12:13], 0, v[120:121]
	global_store_dword v[4:5], v3, off nt
	v_cvt_pk_bf16_f32 v4, v2, v14
	v_lshl_add_u64 v[2:3], v[12:13], 0, v[122:123]
	global_store_dword v[2:3], v4, off nt
	v_cvt_pk_bf16_f32 v2, v15, v0
	v_lshl_add_u64 v[0:1], v[12:13], 0, v[124:125]
	global_store_dword v[0:1], v2, off nt
	s_and_saveexec_b64 s[12:13], s[6:7]
	s_cbranch_execz .LBB0_288
	v_add_u32_e32 v12, 0x1000, v90
	ds_read2_b64 v[0:3], v12 offset0:192 offset1:224
	ds_read2_b64 v[4:7], v12 offset0:128 offset1:160
	ds_read2_b64 v[8:11], v12 offset0:64 offset1:96
	ds_read2_b64 v[12:15], v12 offset1:32
	s_waitcnt lgkmcnt(3)
	v_fma_f32 v16, 0, v2, v3
	v_pk_mul_f32 v[2:3], v[2:3], v[0:1]
	v_fma_f32 v0, v0, v16, v1
	s_waitcnt lgkmcnt(2)
	v_fma_f32 v0, v6, v0, v7
	v_fma_f32 v0, v4, v0, v5
	s_waitcnt lgkmcnt(1)
	v_fma_f32 v1, v10, v0, v11
	v_mov_b32_e32 v0, v2
	v_mov_b32_e32 v16, v6
	v_mov_b32_e32 v17, v8
	v_pk_mul_f32 v[2:3], v[2:3], v[6:7]
	v_pk_fma_f32 v[0:1], v[0:1], v[16:17], v[8:9]
	v_pk_mul_f32 v[2:3], v[2:3], v[4:5]
	s_waitcnt lgkmcnt(0)
	v_mov_b32_e32 v11, v14
	v_mov_b32_e32 v3, v1
	v_pk_mul_f32 v[0:1], v[2:3], v[10:11]
	v_pk_fma_f32 v[2:3], v[2:3], v[10:11], v[14:15]
	v_pk_mul_f32 v[0:1], v[0:1], v[8:9]
	v_mov_b32_e32 v4, v14
	v_mov_b32_e32 v2, v0
	v_mov_b32_e32 v5, v12
	v_pk_mul_f32 v[0:1], v[0:1], v[14:15]
	v_pk_fma_f32 v[2:3], v[2:3], v[4:5], v[12:13]
	v_pk_mul_f32 v[0:1], v[0:1], v[12:13]
	v_add_u32_e32 v2, 64, v92
	v_mov_b32_e32 v1, v3
	v_ashrrev_i32_e32 v3, 31, v2
	v_lshl_add_u64 v[2:3], v[2:3], 3, s[30:31]
	global_store_dwordx2 v[2:3], v[0:1], off

.LBB0_294:
	v_cndmask_b32_e64 v0, 1.0, v35, s[4:5]
	v_cndmask_b32_e64 v35, 0, v37, s[4:5]
	v_fmac_f32_e32 v35, v0, v1
	v_mul_f32_e32 v0, v0, v8
	v_cndmask_b32_e64 v37, v38, v41, s[4:5]
	v_cndmask_b32_e64 v36, v36, v40, s[4:5]
	v_fmac_f32_e32 v36, v37, v1
	v_mul_f32_e32 v37, v37, v8
	v_cndmask_b32_e64 v40, v46, v48, s[4:5]
	v_cndmask_b32_e64 v41, v43, v47, s[4:5]
	v_fmac_f32_e32 v41, v40, v1
	v_mul_f32_e32 v40, v40, v8
	v_fmac_f32_e32 v25, v32, v41
	v_mul_f32_e32 v32, v32, v40
	v_fmac_f32_e32 v23, v29, v41
	v_mul_f32_e32 v29, v29, v40
	v_fmac_f32_e32 v20, v26, v41
	v_mul_f32_e32 v26, v26, v40
	v_fmac_f32_e32 v3, v16, v41
	v_mul_f32_e32 v40, v16, v40
	v_cvt_pk_bf16_f32 v16, v25, v32
	v_cndmask_b32_e64 v38, v42, v45, s[4:5]
	v_cndmask_b32_e64 v39, v39, v44, s[4:5]
	v_fmac_f32_e32 v39, v38, v1
	v_mul_f32_e32 v38, v38, v8
	v_fmac_f32_e32 v10, v34, v36
	v_mul_f32_e32 v34, v34, v37
	v_fmac_f32_e32 v6, v31, v36
	v_mul_f32_e32 v31, v31, v37
	v_fmac_f32_e32 v4, v28, v36
	v_mul_f32_e32 v28, v28, v37
	v_fmac_f32_e32 v11, v18, v36
	v_mul_f32_e32 v18, v18, v37
	v_fmac_f32_e32 v9, v12, v35
	v_mul_f32_e32 v36, v0, v12
	v_fmac_f32_e32 v5, v13, v35
	v_mul_f32_e32 v37, v0, v13
	v_lshl_add_u64 v[12:13], v[94:95], 0, s[62:63]
	global_store_dword v[96:97], v16, off offset:384 nt
	v_fmac_f32_e32 v24, v33, v39
	v_mul_f32_e32 v33, v33, v38
	v_fmac_f32_e32 v21, v30, v39
	v_mul_f32_e32 v30, v30, v38
	v_fmac_f32_e32 v19, v27, v39
	v_mul_f32_e32 v27, v27, v38
	v_fmac_f32_e32 v7, v17, v39
	v_mul_f32_e32 v38, v17, v38
	v_fmac_f32_e32 v2, v14, v35
	v_mul_f32_e32 v14, v0, v14
	v_fmac_f32_e32 v15, v22, v35
	v_mul_f32_e32 v0, v0, v22
	v_cvt_pk_bf16_f32 v22, v23, v29
	v_lshl_add_u64 v[16:17], v[12:13], 0, v[88:89]
	global_store_dword v[16:17], v22, off nt
	v_cvt_pk_bf16_f32 v20, v20, v26
	v_lshl_add_u64 v[16:17], v[12:13], 0, v[98:99]
	global_store_dword v[16:17], v20, off nt
	v_cvt_pk_bf16_f32 v3, v3, v40
	v_lshl_add_u64 v[16:17], v[12:13], 0, v[100:101]
	global_store_dword v[16:17], v3, off nt
	v_cvt_pk_bf16_f32 v3, v24, v33
	v_lshl_add_u64 v[16:17], v[12:13], 0, v[102:103]
	global_store_dword v[16:17], v3, off nt
	v_cvt_pk_bf16_f32 v3, v21, v30
	v_lshl_add_u64 v[16:17], v[12:13], 0, v[104:105]
	global_store_dword v[16:17], v3, off nt
	v_cvt_pk_bf16_f32 v3, v19, v27
	v_lshl_add_u64 v[16:17], v[12:13], 0, v[106:107]
	global_store_dword v[16:17], v3, off nt
	v_cvt_pk_bf16_f32 v3, v7, v38
	v_lshl_add_u64 v[16:17], v[12:13], 0, v[108:109]
	global_store_dword v[16:17], v3, off nt
	v_cvt_pk_bf16_f32 v3, v10, v34
	v_lshl_add_u64 v[16:17], v[12:13], 0, v[110:111]
	global_store_dword v[16:17], v3, off nt
	v_cvt_pk_bf16_f32 v3, v6, v31
	v_lshl_add_u64 v[6:7], v[12:13], 0, v[112:113]
	global_store_dword v[6:7], v3, off nt
	v_cvt_pk_bf16_f32 v3, v4, v28
	v_lshl_add_u64 v[6:7], v[12:13], 0, v[114:115]
	global_store_dword v[6:7], v3, off nt
	v_cvt_pk_bf16_f32 v3, v11, v18
	v_lshl_add_u64 v[6:7], v[12:13], 0, v[116:117]
	global_store_dword v[6:7], v3, off nt
	v_cvt_pk_bf16_f32 v3, v9, v36
	v_lshl_add_u64 v[6:7], v[12:13], 0, v[118:119]
	global_store_dword v[6:7], v3, off nt
	v_cvt_pk_bf16_f32 v3, v5, v37
	v_lshl_add_u64 v[4:5], v[12:13], 0, v[120:121]
	global_store_dword v[4:5], v3, off nt
	v_cvt_pk_bf16_f32 v4, v2, v14
	v_lshl_add_u64 v[2:3], v[12:13], 0, v[122:123]
	global_store_dword v[2:3], v4, off nt
	v_cvt_pk_bf16_f32 v2, v15, v0
	v_lshl_add_u64 v[0:1], v[12:13], 0, v[124:125]
	global_store_dword v[0:1], v2, off nt
	s_and_saveexec_b64 s[4:5], s[6:7]
	s_cbranch_execz .LBB0_244
	v_add_u32_e32 v12, 0x1800, v90
	ds_read2_b64 v[0:3], v12 offset0:192 offset1:224
	ds_read2_b64 v[4:7], v12 offset0:128 offset1:160
	ds_read2_b64 v[8:11], v12 offset0:64 offset1:96
	ds_read2_b64 v[12:15], v12 offset1:32
	s_waitcnt lgkmcnt(3)
	v_fma_f32 v16, 0, v2, v3
	v_pk_mul_f32 v[2:3], v[2:3], v[0:1]
	v_fma_f32 v0, v0, v16, v1
	s_waitcnt lgkmcnt(2)
	v_fma_f32 v0, v6, v0, v7
	v_fma_f32 v0, v4, v0, v5
	s_waitcnt lgkmcnt(1)
	v_fma_f32 v1, v10, v0, v11
	v_mov_b32_e32 v0, v2
	v_mov_b32_e32 v16, v6
	v_mov_b32_e32 v17, v8
	v_pk_mul_f32 v[2:3], v[2:3], v[6:7]
	v_pk_fma_f32 v[0:1], v[0:1], v[16:17], v[8:9]
	v_pk_mul_f32 v[2:3], v[2:3], v[4:5]
	s_waitcnt lgkmcnt(0)
	v_mov_b32_e32 v11, v14
	v_mov_b32_e32 v3, v1
	v_pk_mul_f32 v[0:1], v[2:3], v[10:11]
	v_pk_fma_f32 v[2:3], v[2:3], v[10:11], v[14:15]
	v_pk_mul_f32 v[0:1], v[0:1], v[8:9]
	v_mov_b32_e32 v4, v14
	v_mov_b32_e32 v2, v0
	v_mov_b32_e32 v5, v12
	v_pk_mul_f32 v[0:1], v[0:1], v[14:15]
	v_pk_fma_f32 v[2:3], v[2:3], v[4:5], v[12:13]
	v_pk_mul_f32 v[0:1], v[0:1], v[12:13]
	v_add_u32_e32 v2, 0x60, v92
	v_mov_b32_e32 v1, v3
	v_ashrrev_i32_e32 v3, 31, v2
	v_lshl_add_u64 v[2:3], v[2:3], 3, s[30:31]
	global_store_dwordx2 v[2:3], v[0:1], off
	s_branch .LBB0_244

.LBB0_331:
	v_lshl_add_u64 v[126:127], s[36:37], 0, v[88:89]
	v_lshl_add_u64 v[128:129], s[40:41], 0, v[88:89]
	v_lshl_add_u64 v[130:131], s[42:43], 0, v[88:89]
	v_cndmask_b32_e64 v1, v13, 1.0, s[0:1]
	v_cndmask_b32_e64 v2, v10, 0, s[0:1]
	v_fmac_f32_e32 v2, v1, v3
	v_mul_f32_e32 v1, v1, v0
	v_cndmask_b32_e64 v10, v42, v15, s[0:1]
	v_cndmask_b32_e64 v13, v17, v14, s[0:1]
	v_fmac_f32_e32 v13, v10, v3
	v_mul_f32_e32 v10, v10, v0
	v_cndmask_b32_e64 v14, v46, v43, s[0:1]
	v_cndmask_b32_e64 v15, v44, v41, s[0:1]
	v_fmac_f32_e32 v15, v14, v3
	v_mul_f32_e32 v14, v14, v0
	s_ashr_i32 s9, s8, 31
	v_lshlrev_b32_e32 v88, 2, v94
	v_cndmask_b32_e64 v17, v96, v47, s[0:1]
	v_cndmask_b32_e64 v41, v91, v45, s[0:1]
	v_fmac_f32_e32 v41, v17, v3
	v_mul_f32_e32 v17, v17, v0
	v_fmac_f32_e32 v18, v32, v2
	v_mul_f32_e32 v32, v1, v32
	v_fmac_f32_e32 v31, v33, v2
	v_mul_f32_e32 v33, v1, v33
	v_fmac_f32_e32 v30, v34, v2
	v_mul_f32_e32 v34, v1, v34
	v_fmac_f32_e32 v29, v35, v2
	v_mul_f32_e32 v1, v1, v35
	v_fmac_f32_e32 v19, v20, v13
	v_mul_f32_e32 v2, v20, v10
	v_fmac_f32_e32 v28, v36, v13
	v_mul_f32_e32 v20, v36, v10
	v_fmac_f32_e32 v27, v37, v13
	v_mul_f32_e32 v35, v37, v10
	v_fmac_f32_e32 v26, v38, v13
	v_mul_f32_e32 v10, v38, v10
	v_fmac_f32_e32 v23, v12, v15
	v_mul_f32_e32 v38, v12, v14
	v_lshl_add_u64 v[12:13], s[22:23], 0, v[88:89]
	s_lshl_b64 s[4:5], s[8:9], 12
	v_fmac_f32_e32 v24, v40, v15
	v_mul_f32_e32 v37, v40, v14
	v_fmac_f32_e32 v7, v4, v41
	v_mul_f32_e32 v40, v4, v17
	v_lshl_add_u64 v[94:95], v[12:13], 0, s[4:5]
	v_lshlrev_b32_e32 v12, 14, v93
	v_mov_b32_e32 v13, v89
	v_cvt_pk_bf16_f32 v4, v18, v32
	v_lshl_add_u64 v[96:97], v[94:95], 0, v[12:13]
	global_load_dword v172, v[130:131], off offset:128
	global_load_dword v173, v[126:127], off offset:128
	global_load_dword v174, v[128:129], off offset:128
	global_store_dword v[96:97], v4, off nt
	v_or_b32_e32 v88, 0x1000, v12
	v_fmac_f32_e32 v21, v22, v15
	v_mul_f32_e32 v22, v22, v14
	v_fmac_f32_e32 v25, v39, v15
	v_mul_f32_e32 v36, v39, v14
	v_cvt_pk_bf16_f32 v4, v31, v33
	v_lshl_add_u64 v[14:15], v[94:95], 0, v[88:89]
	v_or_b32_e32 v98, 0x2000, v12
	v_mov_b32_e32 v99, v89
	global_store_dword v[14:15], v4, off nt
	v_lshl_add_u64 v[14:15], v[94:95], 0, v[98:99]
	v_or_b32_e32 v100, 0x3000, v12
	v_mov_b32_e32 v101, v89
	v_cvt_pk_bf16_f32 v4, v30, v34
	global_store_dword v[14:15], v4, off nt
	v_cvt_pk_bf16_f32 v1, v29, v1
	v_lshl_add_u64 v[14:15], v[94:95], 0, v[100:101]
	global_store_dword v[14:15], v1, off nt
	v_or_b32_e32 v102, 0x8000, v12
	v_mov_b32_e32 v103, v89
	v_cvt_pk_bf16_f32 v1, v19, v2
	v_lshl_add_u64 v[14:15], v[94:95], 0, v[102:103]
	global_store_dword v[14:15], v1, off nt
	v_or_b32_e32 v104, 0x9000, v12
	v_mov_b32_e32 v105, v89
	v_cvt_pk_bf16_f32 v1, v28, v20
	v_lshl_add_u64 v[14:15], v[94:95], 0, v[104:105]
	global_store_dword v[14:15], v1, off nt
	v_or_b32_e32 v106, 0xa000, v12
	v_mov_b32_e32 v107, v89
	v_cvt_pk_bf16_f32 v1, v27, v35
	v_lshl_add_u64 v[14:15], v[94:95], 0, v[106:107]
	global_store_dword v[14:15], v1, off nt
	v_or_b32_e32 v108, 0xb000, v12
	v_mov_b32_e32 v109, v89
	v_cvt_pk_bf16_f32 v1, v26, v10
	v_lshl_add_u64 v[14:15], v[94:95], 0, v[108:109]
	global_store_dword v[14:15], v1, off nt
	v_or_b32_e32 v110, 0x10000, v12
	v_mov_b32_e32 v111, v89
	v_cvt_pk_bf16_f32 v1, v21, v22
	v_lshl_add_u64 v[14:15], v[94:95], 0, v[110:111]
	global_store_dword v[14:15], v1, off nt
	v_or_b32_e32 v112, 0x11000, v12
	v_mov_b32_e32 v113, v89
	v_cvt_pk_bf16_f32 v1, v25, v36
	v_lshl_add_u64 v[14:15], v[94:95], 0, v[112:113]
	global_store_dword v[14:15], v1, off nt
	v_or_b32_e32 v114, 0x12000, v12
	v_mov_b32_e32 v115, v89
	v_cvt_pk_bf16_f32 v1, v24, v37
	v_lshl_add_u64 v[14:15], v[94:95], 0, v[114:115]
	global_store_dword v[14:15], v1, off nt
	v_or_b32_e32 v116, 0x13000, v12
	v_mov_b32_e32 v117, v89
	v_fmac_f32_e32 v8, v16, v41
	v_mul_f32_e32 v16, v16, v17
	v_cvt_pk_bf16_f32 v1, v23, v38
	v_lshl_add_u64 v[14:15], v[94:95], 0, v[116:117]
	global_store_dword v[14:15], v1, off nt
	v_or_b32_e32 v118, 0x18000, v12
	v_mov_b32_e32 v119, v89
	v_fmac_f32_e32 v5, v9, v41
	v_mul_f32_e32 v39, v9, v17
	v_cvt_pk_bf16_f32 v1, v8, v16
	v_lshl_add_u64 v[8:9], v[94:95], 0, v[118:119]
	global_store_dword v[8:9], v1, off nt
	v_or_b32_e32 v120, 0x19000, v12
	v_mov_b32_e32 v121, v89
	v_cvt_pk_bf16_f32 v1, v5, v39
	v_lshl_add_u64 v[4:5], v[94:95], 0, v[120:121]
	v_fmac_f32_e32 v11, v6, v41
	v_mul_f32_e32 v6, v6, v17
	s_lshl_b32 s6, s63, 11
	global_store_dword v[4:5], v1, off nt
	v_or_b32_e32 v122, 0x1a000, v12
	v_mov_b32_e32 v123, v89
	s_or_b32 s6, s6, s70
	v_cvt_pk_bf16_f32 v1, v7, v40
	v_lshl_add_u64 v[4:5], v[94:95], 0, v[122:123]
	v_or_b32_e32 v124, 0x1b000, v12
	v_mov_b32_e32 v125, v89
	v_lshl_add_u32 v142, v92, 3, 16
	v_cmp_gt_i32_e64 s[4:5], 32, v92
	v_add_u32_e32 v92, s6, v92
	global_store_dword v[4:5], v1, off nt
	v_cvt_pk_bf16_f32 v2, v11, v6
	v_lshl_add_u64 v[0:1], v[94:95], 0, v[124:125]
	global_store_dword v[0:1], v2, off nt
	s_and_saveexec_b64 s[6:7], s[4:5]
	s_cbranch_execz .LBB0_333
	ds_read2_b64 v[0:3], v142 offset1:32
	ds_read2_b64 v[4:7], v142 offset0:64 offset1:96
	ds_read2_b64 v[8:11], v142 offset0:128 offset1:160
	ds_read2_b64 v[12:15], v142 offset0:192 offset1:224
	v_ashrrev_i32_e32 v93, 31, v92
	s_waitcnt lgkmcnt(3)
	v_fma_f32 v16, 0, v0, v1
	v_pk_mul_f32 v[0:1], v[0:1], v[2:3]
	v_fma_f32 v2, v2, v16, v3
	s_waitcnt lgkmcnt(2)
	v_fma_f32 v2, v4, v2, v5
	v_fma_f32 v2, v6, v2, v7
	s_waitcnt lgkmcnt(1)
	v_fma_f32 v3, v8, v2, v9
	v_mov_b32_e32 v2, v0
	v_mov_b32_e32 v16, v4
	v_mov_b32_e32 v17, v10
	v_pk_mul_f32 v[0:1], v[0:1], v[4:5]
	v_pk_fma_f32 v[2:3], v[2:3], v[16:17], v[10:11]
	v_pk_mul_f32 v[0:1], v[0:1], v[6:7]
	s_waitcnt lgkmcnt(0)
	v_mov_b32_e32 v9, v12
	v_mov_b32_e32 v1, v3
	v_pk_mul_f32 v[2:3], v[0:1], v[8:9]
	v_pk_fma_f32 v[0:1], v[0:1], v[8:9], v[12:13]
	v_pk_mul_f32 v[2:3], v[2:3], v[10:11]
	v_mov_b32_e32 v4, v12
	v_mov_b32_e32 v0, v2
	v_mov_b32_e32 v5, v14
	v_pk_mul_f32 v[2:3], v[2:3], v[12:13]
	v_pk_fma_f32 v[0:1], v[0:1], v[4:5], v[14:15]
	v_pk_mul_f32 v[2:3], v[2:3], v[14:15]
	s_nop 0
	v_mov_b32_e32 v3, v1
	v_lshl_add_u64 v[0:1], v[92:93], 3, s[24:25]
	global_store_dwordx2 v[0:1], v[2:3], off

.LBB0_344:
	v_cndmask_b32_e64 v1, v13, 1.0, s[0:1]
	v_cndmask_b32_e64 v2, v10, 0, s[0:1]
	v_fmac_f32_e32 v2, v1, v3
	v_mul_f32_e32 v1, v1, v0
	v_cndmask_b32_e64 v10, v42, v15, s[0:1]
	v_cndmask_b32_e64 v13, v17, v14, s[0:1]
	v_fmac_f32_e32 v13, v10, v3
	v_mul_f32_e32 v10, v10, v0
	v_cndmask_b32_e64 v14, v46, v43, s[0:1]
	v_cndmask_b32_e64 v15, v44, v41, s[0:1]
	v_fmac_f32_e32 v15, v14, v3
	v_mul_f32_e32 v14, v14, v0
	v_cndmask_b32_e64 v17, v93, v47, s[0:1]
	v_cndmask_b32_e64 v41, v91, v45, s[0:1]
	v_fmac_f32_e32 v41, v17, v3
	v_mul_f32_e32 v17, v17, v0
	v_fmac_f32_e32 v18, v32, v2
	v_mul_f32_e32 v32, v1, v32
	v_fmac_f32_e32 v31, v33, v2
	v_mul_f32_e32 v33, v1, v33
	v_fmac_f32_e32 v30, v34, v2
	v_mul_f32_e32 v34, v1, v34
	v_fmac_f32_e32 v29, v35, v2
	v_mul_f32_e32 v1, v1, v35
	v_fmac_f32_e32 v27, v37, v13
	v_mul_f32_e32 v35, v37, v10
	v_fmac_f32_e32 v24, v40, v15
	v_mul_f32_e32 v37, v40, v14
	v_fmac_f32_e32 v9, v4, v41
	v_mul_f32_e32 v40, v4, v17
	v_cvt_pk_bf16_f32 v4, v18, v32
	v_fmac_f32_e32 v19, v20, v13
	v_mul_f32_e32 v2, v20, v10
	v_fmac_f32_e32 v28, v36, v13
	v_mul_f32_e32 v20, v36, v10
	v_fmac_f32_e32 v26, v38, v13
	v_mul_f32_e32 v10, v38, v10
	v_fmac_f32_e32 v23, v12, v15
	v_mul_f32_e32 v38, v12, v14
	v_lshl_add_u64 v[12:13], v[94:95], 0, s[38:39]
	global_load_dword v172, v[130:131], off offset:256
	global_load_dword v173, v[126:127], off offset:256
	global_load_dword v174, v[128:129], off offset:256
	global_store_dword v[96:97], v4, off offset:128 nt
	v_fmac_f32_e32 v21, v22, v15
	v_mul_f32_e32 v22, v22, v14
	v_fmac_f32_e32 v25, v39, v15
	v_mul_f32_e32 v36, v39, v14
	v_cvt_pk_bf16_f32 v4, v31, v33
	v_lshl_add_u64 v[14:15], v[12:13], 0, v[88:89]
	global_store_dword v[14:15], v4, off nt
	v_lshl_add_u64 v[14:15], v[12:13], 0, v[98:99]
	v_cvt_pk_bf16_f32 v4, v30, v34
	global_store_dword v[14:15], v4, off nt
	v_cvt_pk_bf16_f32 v1, v29, v1
	v_lshl_add_u64 v[14:15], v[12:13], 0, v[100:101]
	global_store_dword v[14:15], v1, off nt
	v_cvt_pk_bf16_f32 v1, v19, v2
	v_lshl_add_u64 v[14:15], v[12:13], 0, v[102:103]
	global_store_dword v[14:15], v1, off nt
	v_cvt_pk_bf16_f32 v1, v28, v20
	v_lshl_add_u64 v[14:15], v[12:13], 0, v[104:105]
	global_store_dword v[14:15], v1, off nt
	v_cvt_pk_bf16_f32 v1, v27, v35
	v_lshl_add_u64 v[14:15], v[12:13], 0, v[106:107]
	global_store_dword v[14:15], v1, off nt
	v_cvt_pk_bf16_f32 v1, v26, v10
	v_lshl_add_u64 v[14:15], v[12:13], 0, v[108:109]
	global_store_dword v[14:15], v1, off nt
	v_cvt_pk_bf16_f32 v1, v21, v22
	v_lshl_add_u64 v[14:15], v[12:13], 0, v[110:111]
	global_store_dword v[14:15], v1, off nt
	v_cvt_pk_bf16_f32 v1, v25, v36
	v_lshl_add_u64 v[14:15], v[12:13], 0, v[112:113]
	global_store_dword v[14:15], v1, off nt
	v_cvt_pk_bf16_f32 v1, v24, v37
	v_lshl_add_u64 v[14:15], v[12:13], 0, v[114:115]
	global_store_dword v[14:15], v1, off nt
	v_fmac_f32_e32 v6, v16, v41
	v_mul_f32_e32 v16, v16, v17
	v_cvt_pk_bf16_f32 v1, v23, v38
	v_lshl_add_u64 v[14:15], v[12:13], 0, v[116:117]
	global_store_dword v[14:15], v1, off nt
	v_fmac_f32_e32 v5, v7, v41
	v_mul_f32_e32 v39, v7, v17
	v_cvt_pk_bf16_f32 v1, v6, v16
	v_lshl_add_u64 v[6:7], v[12:13], 0, v[118:119]
	global_store_dword v[6:7], v1, off nt
	v_cvt_pk_bf16_f32 v1, v5, v39
	v_lshl_add_u64 v[4:5], v[12:13], 0, v[120:121]
	v_fmac_f32_e32 v11, v8, v41
	v_mul_f32_e32 v8, v8, v17
	global_store_dword v[4:5], v1, off nt
	v_cvt_pk_bf16_f32 v1, v9, v40
	v_lshl_add_u64 v[4:5], v[12:13], 0, v[122:123]
	global_store_dword v[4:5], v1, off nt
	v_cvt_pk_bf16_f32 v2, v11, v8
	v_lshl_add_u64 v[0:1], v[12:13], 0, v[124:125]
	global_store_dword v[0:1], v2, off nt
	s_and_saveexec_b64 s[8:9], s[4:5]
	s_cbranch_execz .LBB0_346
	v_add_u32_e32 v12, 0x800, v142
	ds_read2_b64 v[0:3], v12 offset1:32
	ds_read2_b64 v[4:7], v12 offset0:64 offset1:96
	ds_read2_b64 v[8:11], v12 offset0:128 offset1:160
	ds_read2_b64 v[12:15], v12 offset0:192 offset1:224
	s_waitcnt lgkmcnt(3)
	v_fma_f32 v16, 0, v0, v1
	v_pk_mul_f32 v[0:1], v[0:1], v[2:3]
	v_fma_f32 v2, v2, v16, v3
	s_waitcnt lgkmcnt(2)
	v_fma_f32 v2, v4, v2, v5
	v_fma_f32 v2, v6, v2, v7
	s_waitcnt lgkmcnt(1)
	v_fma_f32 v3, v8, v2, v9
	v_mov_b32_e32 v2, v0
	v_mov_b32_e32 v16, v4
	v_mov_b32_e32 v17, v10
	v_pk_mul_f32 v[0:1], v[0:1], v[4:5]
	v_pk_fma_f32 v[2:3], v[2:3], v[16:17], v[10:11]
	v_pk_mul_f32 v[0:1], v[0:1], v[6:7]
	s_waitcnt lgkmcnt(0)
	v_mov_b32_e32 v9, v12
	v_mov_b32_e32 v1, v3
	v_pk_mul_f32 v[2:3], v[0:1], v[8:9]
	v_pk_fma_f32 v[0:1], v[0:1], v[8:9], v[12:13]
	v_pk_mul_f32 v[2:3], v[2:3], v[10:11]
	v_mov_b32_e32 v4, v12
	v_mov_b32_e32 v0, v2
	v_mov_b32_e32 v5, v14
	v_pk_mul_f32 v[2:3], v[2:3], v[12:13]
	v_pk_fma_f32 v[0:1], v[0:1], v[4:5], v[14:15]
	v_pk_mul_f32 v[2:3], v[2:3], v[14:15]
	v_add_u32_e32 v0, 32, v92
	v_mov_b32_e32 v3, v1
	v_ashrrev_i32_e32 v1, 31, v0
	v_lshl_add_u64 v[0:1], v[0:1], 3, s[24:25]
	global_store_dwordx2 v[0:1], v[2:3], off

.LBB0_357:
	v_cndmask_b32_e64 v1, v13, 1.0, s[0:1]
	v_cndmask_b32_e64 v2, v10, 0, s[0:1]
	v_fmac_f32_e32 v2, v1, v3
	v_mul_f32_e32 v1, v1, v0
	v_cndmask_b32_e64 v10, v42, v15, s[0:1]
	v_cndmask_b32_e64 v13, v17, v14, s[0:1]
	v_fmac_f32_e32 v13, v10, v3
	v_mul_f32_e32 v10, v10, v0
	v_cndmask_b32_e64 v14, v46, v43, s[0:1]
	v_cndmask_b32_e64 v15, v44, v41, s[0:1]
	v_fmac_f32_e32 v15, v14, v3
	v_mul_f32_e32 v14, v14, v0
	v_cndmask_b32_e64 v17, v93, v47, s[0:1]
	v_cndmask_b32_e64 v41, v91, v45, s[0:1]
	v_fmac_f32_e32 v41, v17, v3
	v_mul_f32_e32 v17, v17, v0
	v_fmac_f32_e32 v18, v32, v2
	v_mul_f32_e32 v32, v1, v32
	v_fmac_f32_e32 v31, v33, v2
	v_mul_f32_e32 v33, v1, v33
	v_fmac_f32_e32 v30, v34, v2
	v_mul_f32_e32 v34, v1, v34
	v_fmac_f32_e32 v29, v35, v2
	v_mul_f32_e32 v1, v1, v35
	v_fmac_f32_e32 v27, v37, v13
	v_mul_f32_e32 v35, v37, v10
	v_fmac_f32_e32 v24, v40, v15
	v_mul_f32_e32 v37, v40, v14
	v_fmac_f32_e32 v9, v4, v41
	v_mul_f32_e32 v40, v4, v17
	v_cvt_pk_bf16_f32 v4, v18, v32
	v_fmac_f32_e32 v19, v20, v13
	v_mul_f32_e32 v2, v20, v10
	v_fmac_f32_e32 v28, v36, v13
	v_mul_f32_e32 v20, v36, v10
	v_fmac_f32_e32 v26, v38, v13
	v_mul_f32_e32 v10, v38, v10
	v_fmac_f32_e32 v23, v12, v15
	v_mul_f32_e32 v38, v12, v14
	v_lshl_add_u64 v[12:13], v[94:95], 0, s[48:49]
	global_load_dword v172, v[130:131], off offset:384
	global_load_dword v173, v[126:127], off offset:384
	global_load_dword v174, v[128:129], off offset:384
	global_store_dword v[96:97], v4, off offset:256 nt
	v_fmac_f32_e32 v21, v22, v15
	v_mul_f32_e32 v22, v22, v14
	v_fmac_f32_e32 v25, v39, v15
	v_mul_f32_e32 v36, v39, v14
	v_cvt_pk_bf16_f32 v4, v31, v33
	v_lshl_add_u64 v[14:15], v[12:13], 0, v[88:89]
	global_store_dword v[14:15], v4, off nt
	v_lshl_add_u64 v[14:15], v[12:13], 0, v[98:99]
	v_cvt_pk_bf16_f32 v4, v30, v34
	global_store_dword v[14:15], v4, off nt
	v_cvt_pk_bf16_f32 v1, v29, v1
	v_lshl_add_u64 v[14:15], v[12:13], 0, v[100:101]
	global_store_dword v[14:15], v1, off nt
	v_cvt_pk_bf16_f32 v1, v19, v2
	v_lshl_add_u64 v[14:15], v[12:13], 0, v[102:103]
	global_store_dword v[14:15], v1, off nt
	v_cvt_pk_bf16_f32 v1, v28, v20
	v_lshl_add_u64 v[14:15], v[12:13], 0, v[104:105]
	global_store_dword v[14:15], v1, off nt
	v_cvt_pk_bf16_f32 v1, v27, v35
	v_lshl_add_u64 v[14:15], v[12:13], 0, v[106:107]
	global_store_dword v[14:15], v1, off nt
	v_cvt_pk_bf16_f32 v1, v26, v10
	v_lshl_add_u64 v[14:15], v[12:13], 0, v[108:109]
	global_store_dword v[14:15], v1, off nt
	v_cvt_pk_bf16_f32 v1, v21, v22
	v_lshl_add_u64 v[14:15], v[12:13], 0, v[110:111]
	global_store_dword v[14:15], v1, off nt
	v_cvt_pk_bf16_f32 v1, v25, v36
	v_lshl_add_u64 v[14:15], v[12:13], 0, v[112:113]
	global_store_dword v[14:15], v1, off nt
	v_cvt_pk_bf16_f32 v1, v24, v37
	v_lshl_add_u64 v[14:15], v[12:13], 0, v[114:115]
	global_store_dword v[14:15], v1, off nt
	v_fmac_f32_e32 v6, v16, v41
	v_mul_f32_e32 v16, v16, v17
	v_cvt_pk_bf16_f32 v1, v23, v38
	v_lshl_add_u64 v[14:15], v[12:13], 0, v[116:117]
	global_store_dword v[14:15], v1, off nt
	v_fmac_f32_e32 v5, v7, v41
	v_mul_f32_e32 v39, v7, v17
	v_cvt_pk_bf16_f32 v1, v6, v16
	v_lshl_add_u64 v[6:7], v[12:13], 0, v[118:119]
	global_store_dword v[6:7], v1, off nt
	v_cvt_pk_bf16_f32 v1, v5, v39
	v_lshl_add_u64 v[4:5], v[12:13], 0, v[120:121]
	v_fmac_f32_e32 v11, v8, v41
	v_mul_f32_e32 v8, v8, v17
	global_store_dword v[4:5], v1, off nt
	v_cvt_pk_bf16_f32 v1, v9, v40
	v_lshl_add_u64 v[4:5], v[12:13], 0, v[122:123]
	global_store_dword v[4:5], v1, off nt
	v_cvt_pk_bf16_f32 v2, v11, v8
	v_lshl_add_u64 v[0:1], v[12:13], 0, v[124:125]
	global_store_dword v[0:1], v2, off nt
	s_and_saveexec_b64 s[8:9], s[4:5]
	s_cbranch_execz .LBB0_359
	v_add_u32_e32 v12, 0x1000, v142
	ds_read2_b64 v[0:3], v12 offset1:32
	ds_read2_b64 v[4:7], v12 offset0:64 offset1:96
	ds_read2_b64 v[8:11], v12 offset0:128 offset1:160
	ds_read2_b64 v[12:15], v12 offset0:192 offset1:224
	s_waitcnt lgkmcnt(3)
	v_fma_f32 v16, 0, v0, v1
	v_pk_mul_f32 v[0:1], v[0:1], v[2:3]
	v_fma_f32 v2, v2, v16, v3
	s_waitcnt lgkmcnt(2)
	v_fma_f32 v2, v4, v2, v5
	v_fma_f32 v2, v6, v2, v7
	s_waitcnt lgkmcnt(1)
	v_fma_f32 v3, v8, v2, v9
	v_mov_b32_e32 v2, v0
	v_mov_b32_e32 v16, v4
	v_mov_b32_e32 v17, v10
	v_pk_mul_f32 v[0:1], v[0:1], v[4:5]
	v_pk_fma_f32 v[2:3], v[2:3], v[16:17], v[10:11]
	v_pk_mul_f32 v[0:1], v[0:1], v[6:7]
	s_waitcnt lgkmcnt(0)
	v_mov_b32_e32 v9, v12
	v_mov_b32_e32 v1, v3
	v_pk_mul_f32 v[2:3], v[0:1], v[8:9]
	v_pk_fma_f32 v[0:1], v[0:1], v[8:9], v[12:13]
	v_pk_mul_f32 v[2:3], v[2:3], v[10:11]
	v_mov_b32_e32 v4, v12
	v_mov_b32_e32 v0, v2
	v_mov_b32_e32 v5, v14
	v_pk_mul_f32 v[2:3], v[2:3], v[12:13]
	v_pk_fma_f32 v[0:1], v[0:1], v[4:5], v[14:15]
	v_pk_mul_f32 v[2:3], v[2:3], v[14:15]
	v_add_u32_e32 v0, 64, v92
	v_mov_b32_e32 v3, v1
	v_ashrrev_i32_e32 v1, 31, v0
	v_lshl_add_u64 v[0:1], v[0:1], 3, s[24:25]
	global_store_dwordx2 v[0:1], v[2:3], off

.LBB0_370:
	v_cndmask_b32_e64 v1, v13, 1.0, s[0:1]
	v_cndmask_b32_e64 v2, v10, 0, s[0:1]
	v_fmac_f32_e32 v2, v1, v3
	v_mul_f32_e32 v1, v1, v0
	v_cndmask_b32_e64 v10, v42, v15, s[0:1]
	v_cndmask_b32_e64 v13, v17, v14, s[0:1]
	v_fmac_f32_e32 v13, v10, v3
	v_mul_f32_e32 v10, v10, v0
	v_cndmask_b32_e64 v14, v46, v43, s[0:1]
	v_cndmask_b32_e64 v15, v44, v41, s[0:1]
	v_fmac_f32_e32 v15, v14, v3
	v_mul_f32_e32 v14, v14, v0
	v_cndmask_b32_e64 v17, v49, v47, s[0:1]
	v_cndmask_b32_e64 v41, v48, v45, s[0:1]
	v_fmac_f32_e32 v41, v17, v3
	v_mul_f32_e32 v17, v17, v0
	v_fmac_f32_e32 v18, v32, v2
	v_mul_f32_e32 v32, v1, v32
	v_fmac_f32_e32 v31, v33, v2
	v_mul_f32_e32 v33, v1, v33
	v_fmac_f32_e32 v30, v34, v2
	v_mul_f32_e32 v34, v1, v34
	v_fmac_f32_e32 v29, v35, v2
	v_mul_f32_e32 v1, v1, v35
	v_fmac_f32_e32 v27, v37, v13
	v_mul_f32_e32 v35, v37, v10
	v_fmac_f32_e32 v24, v40, v15
	v_mul_f32_e32 v37, v40, v14
	v_fmac_f32_e32 v9, v4, v41
	v_mul_f32_e32 v40, v4, v17
	v_cvt_pk_bf16_f32 v4, v18, v32
	v_fmac_f32_e32 v19, v20, v13
	v_mul_f32_e32 v2, v20, v10
	v_fmac_f32_e32 v28, v36, v13
	v_mul_f32_e32 v20, v36, v10
	v_fmac_f32_e32 v26, v38, v13
	v_mul_f32_e32 v10, v38, v10
	v_fmac_f32_e32 v23, v12, v15
	v_mul_f32_e32 v38, v12, v14
	v_lshl_add_u64 v[12:13], v[94:95], 0, s[60:61]
	global_store_dword v[96:97], v4, off offset:384 nt
	v_fmac_f32_e32 v21, v22, v15
	v_mul_f32_e32 v22, v22, v14
	v_fmac_f32_e32 v25, v39, v15
	v_mul_f32_e32 v36, v39, v14
	v_cvt_pk_bf16_f32 v4, v31, v33
	v_lshl_add_u64 v[14:15], v[12:13], 0, v[88:89]
	global_store_dword v[14:15], v4, off nt
	v_lshl_add_u64 v[14:15], v[12:13], 0, v[98:99]
	v_cvt_pk_bf16_f32 v4, v30, v34
	global_store_dword v[14:15], v4, off nt
	v_cvt_pk_bf16_f32 v1, v29, v1
	v_lshl_add_u64 v[14:15], v[12:13], 0, v[100:101]
	global_store_dword v[14:15], v1, off nt
	v_cvt_pk_bf16_f32 v1, v19, v2
	v_lshl_add_u64 v[14:15], v[12:13], 0, v[102:103]
	global_store_dword v[14:15], v1, off nt
	v_cvt_pk_bf16_f32 v1, v28, v20
	v_lshl_add_u64 v[14:15], v[12:13], 0, v[104:105]
	global_store_dword v[14:15], v1, off nt
	v_cvt_pk_bf16_f32 v1, v27, v35
	v_lshl_add_u64 v[14:15], v[12:13], 0, v[106:107]
	global_store_dword v[14:15], v1, off nt
	v_cvt_pk_bf16_f32 v1, v26, v10
	v_lshl_add_u64 v[14:15], v[12:13], 0, v[108:109]
	global_store_dword v[14:15], v1, off nt
	v_cvt_pk_bf16_f32 v1, v21, v22
	v_lshl_add_u64 v[14:15], v[12:13], 0, v[110:111]
	global_store_dword v[14:15], v1, off nt
	v_cvt_pk_bf16_f32 v1, v25, v36
	v_lshl_add_u64 v[14:15], v[12:13], 0, v[112:113]
	global_store_dword v[14:15], v1, off nt
	v_cvt_pk_bf16_f32 v1, v24, v37
	v_lshl_add_u64 v[14:15], v[12:13], 0, v[114:115]
	global_store_dword v[14:15], v1, off nt
	v_fmac_f32_e32 v6, v16, v41
	v_mul_f32_e32 v16, v16, v17
	v_cvt_pk_bf16_f32 v1, v23, v38
	v_lshl_add_u64 v[14:15], v[12:13], 0, v[116:117]
	global_store_dword v[14:15], v1, off nt
	v_fmac_f32_e32 v5, v7, v41
	v_mul_f32_e32 v39, v7, v17
	v_cvt_pk_bf16_f32 v1, v6, v16
	v_lshl_add_u64 v[6:7], v[12:13], 0, v[118:119]
	global_store_dword v[6:7], v1, off nt
	v_cvt_pk_bf16_f32 v1, v5, v39
	v_lshl_add_u64 v[4:5], v[12:13], 0, v[120:121]
	v_fmac_f32_e32 v11, v8, v41
	v_mul_f32_e32 v8, v8, v17
	global_store_dword v[4:5], v1, off nt
	v_cvt_pk_bf16_f32 v1, v9, v40
	v_lshl_add_u64 v[4:5], v[12:13], 0, v[122:123]
	global_store_dword v[4:5], v1, off nt
	v_cvt_pk_bf16_f32 v2, v11, v8
	v_lshl_add_u64 v[0:1], v[12:13], 0, v[124:125]
	global_store_dword v[0:1], v2, off nt
	s_and_saveexec_b64 s[0:1], s[4:5]
	s_cbranch_execz .LBB0_300
	v_add_u32_e32 v12, 0x1800, v142
	ds_read2_b64 v[0:3], v12 offset1:32
	ds_read2_b64 v[4:7], v12 offset0:64 offset1:96
	ds_read2_b64 v[8:11], v12 offset0:128 offset1:160
	ds_read2_b64 v[12:15], v12 offset0:192 offset1:224
	s_waitcnt lgkmcnt(3)
	v_fma_f32 v16, 0, v0, v1
	v_pk_mul_f32 v[0:1], v[0:1], v[2:3]
	v_fma_f32 v2, v2, v16, v3
	s_waitcnt lgkmcnt(2)
	v_fma_f32 v2, v4, v2, v5
	v_fma_f32 v2, v6, v2, v7
	s_waitcnt lgkmcnt(1)
	v_fma_f32 v3, v8, v2, v9
	v_mov_b32_e32 v2, v0
	v_mov_b32_e32 v16, v4
	v_mov_b32_e32 v17, v10
	v_pk_mul_f32 v[0:1], v[0:1], v[4:5]
	v_pk_fma_f32 v[2:3], v[2:3], v[16:17], v[10:11]
	v_pk_mul_f32 v[0:1], v[0:1], v[6:7]
	s_waitcnt lgkmcnt(0)
	v_mov_b32_e32 v9, v12
	v_mov_b32_e32 v1, v3
	v_pk_mul_f32 v[2:3], v[0:1], v[8:9]
	v_pk_fma_f32 v[0:1], v[0:1], v[8:9], v[12:13]
	v_pk_mul_f32 v[2:3], v[2:3], v[10:11]
	v_mov_b32_e32 v4, v12
	v_mov_b32_e32 v0, v2
	v_mov_b32_e32 v5, v14
	v_pk_mul_f32 v[2:3], v[2:3], v[12:13]
	v_pk_fma_f32 v[0:1], v[0:1], v[4:5], v[14:15]
	v_pk_mul_f32 v[2:3], v[2:3], v[14:15]
	v_add_u32_e32 v0, 0x60, v92
	v_mov_b32_e32 v3, v1
	v_ashrrev_i32_e32 v1, 31, v0
	v_lshl_add_u64 v[0:1], v[0:1], 3, s[24:25]
	global_store_dwordx2 v[0:1], v[2:3], off
	s_branch .LBB0_300
